# v16
# speedup vs baseline: 1.0104x; 1.0104x over previous
.LBB0_435:
	v_mul_f32_e32 v176, 0xbfb8aa3b, v126
	v_mul_f32_e32 v177, 0xbfb8aa3b, v127
	v_mul_f32_e32 v178, 0xbfb8aa3b, v128
	v_mul_f32_e32 v179, 0xbfb8aa3b, v129
	v_mul_f32_e32 v180, 0xbfb8aa3b, v118
	v_mul_f32_e32 v181, 0xbfb8aa3b, v119
	v_mul_f32_e32 v182, 0xbfb8aa3b, v120
	v_mul_f32_e32 v183, 0xbfb8aa3b, v121
	v_exp_f32_e32 v176, v176
	v_exp_f32_e32 v177, v177
	v_exp_f32_e32 v178, v178
	v_exp_f32_e32 v179, v179
	v_exp_f32_e32 v180, v180
	v_exp_f32_e32 v181, v181
	v_exp_f32_e32 v182, v182
	v_exp_f32_e32 v183, v183
	v_add_f32_e32 v176, 1.0, v176
	v_add_f32_e32 v177, 1.0, v177
	v_add_f32_e32 v178, 1.0, v178
	v_add_f32_e32 v179, 1.0, v179
	v_add_f32_e32 v180, 1.0, v180
	v_add_f32_e32 v181, 1.0, v181
	v_add_f32_e32 v182, 1.0, v182
	v_add_f32_e32 v183, 1.0, v183
	v_rcp_f32_e32 v176, v176
	v_rcp_f32_e32 v177, v177
	v_rcp_f32_e32 v178, v178
	v_rcp_f32_e32 v179, v179
	v_rcp_f32_e32 v180, v180
	v_rcp_f32_e32 v181, v181
	v_rcp_f32_e32 v182, v182
	v_rcp_f32_e32 v183, v183
	v_mul_f32_e32 v176, v126, v176
	v_mul_f32_e32 v177, v127, v177
	v_mul_f32_e32 v178, v128, v178
	v_mul_f32_e32 v179, v129, v179
	v_mul_f32_e32 v180, v118, v180
	v_mul_f32_e32 v181, v119, v181
	v_mul_f32_e32 v182, v120, v182
	v_mul_f32_e32 v183, v121, v183
	s_lshl_b32 s6, s48, 8
	v_add_u32_e32 v154, s6, v144
	v_mov_b64_e32 v[142:143], s[22:23]
	v_mad_i64_i32 v[154:155], s[48:49], v154, s16, v[142:143]
	s_lshl_b32 s48, s9, 7
	v_mul_f32_e32 v122, v176, v122
	s_ashr_i32 s49, s48, 31
	s_lshl_b64 s[48:49], s[48:49], 1
	v_lshl_add_u64 v[154:155], v[154:155], 0, s[48:49]
	v_lshl_add_u64 v[154:155], v[154:155], 0, s[26:27]
	v_readlane_b32 s80, v254, 35
	s_andn2_b64 vcc, exec, s[38:39]
	v_mul_f32_e32 v123, v177, v123
	v_readlane_b32 s81, v254, 36
	v_readlane_b32 s82, v254, 37
	v_readlane_b32 s83, v254, 38
	v_readlane_b32 s84, v254, 39
	v_readlane_b32 s85, v254, 40
	v_readlane_b32 s86, v254, 41
	v_mul_f32_e32 v124, v178, v124
	v_readlane_b32 s87, v254, 42
	v_readlane_b32 s88, v254, 43
	v_readlane_b32 s89, v254, 44
	v_readlane_b32 s90, v254, 45
	v_readlane_b32 s91, v254, 46
	v_readlane_b32 s92, v254, 47
	v_mul_f32_e32 v125, v179, v125
	v_readlane_b32 s93, v254, 48
	v_readlane_b32 s94, v254, 49
	v_readlane_b32 s95, v254, 50
	v_mul_f32_e32 v126, v180, v114
	v_mul_f32_e32 v127, v181, v115
	v_lshl_add_u64 v[118:119], v[154:155], 0, v[0:1]
	v_mul_f32_e32 v120, v182, v116
	v_mul_f32_e32 v117, v183, v117
	v_cvt_pk_bf16_f32 v114, v122, v123
	v_cvt_pk_bf16_f32 v115, v124, v125
	v_cvt_pk_bf16_f32 v116, v126, v127
	v_cvt_pk_bf16_f32 v117, v120, v117
	flat_store_dwordx4 v[118:119], v[114:117]
	s_nop 1
	v_mul_f32_e32 v176, 0xbfb8aa3b, v110
	v_mul_f32_e32 v177, 0xbfb8aa3b, v111
	v_mul_f32_e32 v178, 0xbfb8aa3b, v112
	v_mul_f32_e32 v179, 0xbfb8aa3b, v113
	v_mul_f32_e32 v180, 0xbfb8aa3b, v102
	v_mul_f32_e32 v181, 0xbfb8aa3b, v103
	v_mul_f32_e32 v182, 0xbfb8aa3b, v104
	v_mul_f32_e32 v183, 0xbfb8aa3b, v105
	v_exp_f32_e32 v176, v176
	v_exp_f32_e32 v177, v177
	v_exp_f32_e32 v178, v178
	v_exp_f32_e32 v179, v179
	v_exp_f32_e32 v180, v180
	v_exp_f32_e32 v181, v181
	v_exp_f32_e32 v182, v182
	v_exp_f32_e32 v183, v183
	v_add_f32_e32 v176, 1.0, v176
	v_add_f32_e32 v177, 1.0, v177
	v_add_f32_e32 v178, 1.0, v178
	v_add_f32_e32 v179, 1.0, v179
	v_add_f32_e32 v180, 1.0, v180
	v_add_f32_e32 v181, 1.0, v181
	v_add_f32_e32 v182, 1.0, v182
	v_add_f32_e32 v183, 1.0, v183
	v_rcp_f32_e32 v176, v176
	v_rcp_f32_e32 v177, v177
	v_rcp_f32_e32 v178, v178
	v_rcp_f32_e32 v179, v179
	v_rcp_f32_e32 v180, v180
	v_rcp_f32_e32 v181, v181
	v_rcp_f32_e32 v182, v182
	v_rcp_f32_e32 v183, v183
	v_mul_f32_e32 v176, v110, v176
	v_mul_f32_e32 v177, v111, v177
	v_mul_f32_e32 v178, v112, v178
	v_mul_f32_e32 v179, v113, v179
	v_mul_f32_e32 v180, v102, v180
	v_mul_f32_e32 v181, v103, v181
	v_mul_f32_e32 v182, v104, v182
	v_mul_f32_e32 v183, v105, v183
	v_add_u32_e32 v114, s6, v146
	v_mad_i64_i32 v[114:115], s[50:51], v114, s16, v[142:143]
	v_lshl_add_u64 v[114:115], v[114:115], 0, s[48:49]
	v_lshl_add_u64 v[114:115], v[114:115], 0, s[26:27]
	v_mul_f32_e32 v106, v176, v106
	v_mul_f32_e32 v107, v177, v107
	v_mul_f32_e32 v108, v178, v108
	v_mul_f32_e32 v109, v179, v109
	v_mul_f32_e32 v110, v180, v98
	v_mul_f32_e32 v111, v181, v99
	v_lshl_add_u64 v[102:103], v[114:115], 0, v[0:1]
	v_mul_f32_e32 v104, v182, v100
	v_mul_f32_e32 v101, v183, v101
	v_cvt_pk_bf16_f32 v98, v106, v107
	v_cvt_pk_bf16_f32 v99, v108, v109
	v_cvt_pk_bf16_f32 v100, v110, v111
	v_cvt_pk_bf16_f32 v101, v104, v101
	flat_store_dwordx4 v[102:103], v[98:101]
	s_nop 1
	v_mul_f32_e32 v176, 0xbfb8aa3b, v94
	v_mul_f32_e32 v177, 0xbfb8aa3b, v95
	v_mul_f32_e32 v178, 0xbfb8aa3b, v96
	v_mul_f32_e32 v179, 0xbfb8aa3b, v97
	v_mul_f32_e32 v180, 0xbfb8aa3b, v86
	v_mul_f32_e32 v181, 0xbfb8aa3b, v87
	v_mul_f32_e32 v182, 0xbfb8aa3b, v88
	v_mul_f32_e32 v183, 0xbfb8aa3b, v89
	v_exp_f32_e32 v176, v176
	v_exp_f32_e32 v177, v177
	v_exp_f32_e32 v178, v178
	v_exp_f32_e32 v179, v179
	v_exp_f32_e32 v180, v180
	v_exp_f32_e32 v181, v181
	v_exp_f32_e32 v182, v182
	v_exp_f32_e32 v183, v183
	v_add_f32_e32 v176, 1.0, v176
	v_add_f32_e32 v177, 1.0, v177
	v_add_f32_e32 v178, 1.0, v178
	v_add_f32_e32 v179, 1.0, v179
	v_add_f32_e32 v180, 1.0, v180
	v_add_f32_e32 v181, 1.0, v181
	v_add_f32_e32 v182, 1.0, v182
	v_add_f32_e32 v183, 1.0, v183
	v_rcp_f32_e32 v176, v176
	v_rcp_f32_e32 v177, v177
	v_rcp_f32_e32 v178, v178
	v_rcp_f32_e32 v179, v179
	v_rcp_f32_e32 v180, v180
	v_rcp_f32_e32 v181, v181
	v_rcp_f32_e32 v182, v182
	v_rcp_f32_e32 v183, v183
	v_mul_f32_e32 v176, v94, v176
	v_mul_f32_e32 v177, v95, v177
	v_mul_f32_e32 v178, v96, v178
	v_mul_f32_e32 v179, v97, v179
	v_mul_f32_e32 v180, v86, v180
	v_mul_f32_e32 v181, v87, v181
	v_mul_f32_e32 v182, v88, v182
	v_mul_f32_e32 v183, v89, v183
	v_add_u32_e32 v98, s6, v147
	v_mad_i64_i32 v[98:99], s[50:51], v98, s16, v[142:143]
	v_lshl_add_u64 v[98:99], v[98:99], 0, s[48:49]
	v_lshl_add_u64 v[98:99], v[98:99], 0, s[26:27]
	v_mul_f32_e32 v90, v176, v90
	v_mul_f32_e32 v91, v177, v91
	v_mul_f32_e32 v92, v178, v92
	v_mul_f32_e32 v93, v179, v93
	v_mul_f32_e32 v94, v180, v82
	v_mul_f32_e32 v95, v181, v83
	v_lshl_add_u64 v[86:87], v[98:99], 0, v[0:1]
	v_mul_f32_e32 v88, v182, v84
	v_mul_f32_e32 v85, v183, v85
	v_cvt_pk_bf16_f32 v82, v90, v91
	v_cvt_pk_bf16_f32 v83, v92, v93
	v_cvt_pk_bf16_f32 v84, v94, v95
	v_cvt_pk_bf16_f32 v85, v88, v85
	flat_store_dwordx4 v[86:87], v[82:85]
	s_nop 1
	v_mul_f32_e32 v176, 0xbfb8aa3b, v78
	v_mul_f32_e32 v177, 0xbfb8aa3b, v79
	v_mul_f32_e32 v178, 0xbfb8aa3b, v80
	v_mul_f32_e32 v179, 0xbfb8aa3b, v81
	v_mul_f32_e32 v180, 0xbfb8aa3b, v70
	v_mul_f32_e32 v181, 0xbfb8aa3b, v71
	v_mul_f32_e32 v182, 0xbfb8aa3b, v72
	v_mul_f32_e32 v183, 0xbfb8aa3b, v73
	v_exp_f32_e32 v176, v176
	v_exp_f32_e32 v177, v177
	v_exp_f32_e32 v178, v178
	v_exp_f32_e32 v179, v179
	v_exp_f32_e32 v180, v180
	v_exp_f32_e32 v181, v181
	v_exp_f32_e32 v182, v182
	v_exp_f32_e32 v183, v183
	v_add_f32_e32 v176, 1.0, v176
	v_add_f32_e32 v177, 1.0, v177
	v_add_f32_e32 v178, 1.0, v178
	v_add_f32_e32 v179, 1.0, v179
	v_add_f32_e32 v180, 1.0, v180
	v_add_f32_e32 v181, 1.0, v181
	v_add_f32_e32 v182, 1.0, v182
	v_add_f32_e32 v183, 1.0, v183
	v_rcp_f32_e32 v176, v176
	v_rcp_f32_e32 v177, v177
	v_rcp_f32_e32 v178, v178
	v_rcp_f32_e32 v179, v179
	v_rcp_f32_e32 v180, v180
	v_rcp_f32_e32 v181, v181
	v_rcp_f32_e32 v182, v182
	v_rcp_f32_e32 v183, v183
	v_mul_f32_e32 v176, v78, v176
	v_mul_f32_e32 v177, v79, v177
	v_mul_f32_e32 v178, v80, v178
	v_mul_f32_e32 v179, v81, v179
	v_mul_f32_e32 v180, v70, v180
	v_mul_f32_e32 v181, v71, v181
	v_mul_f32_e32 v182, v72, v182
	v_mul_f32_e32 v183, v73, v183
	v_add_u32_e32 v82, s6, v148
	v_mad_i64_i32 v[82:83], s[50:51], v82, s16, v[142:143]
	v_lshl_add_u64 v[82:83], v[82:83], 0, s[48:49]
	v_lshl_add_u64 v[82:83], v[82:83], 0, s[26:27]
	v_mul_f32_e32 v74, v176, v74
	v_mul_f32_e32 v75, v177, v75
	v_mul_f32_e32 v76, v178, v76
	v_mul_f32_e32 v77, v179, v77
	v_mul_f32_e32 v78, v180, v66
	v_mul_f32_e32 v79, v181, v67
	v_lshl_add_u64 v[70:71], v[82:83], 0, v[0:1]
	v_mul_f32_e32 v72, v182, v68
	v_mul_f32_e32 v69, v183, v69
	v_cvt_pk_bf16_f32 v66, v74, v75
	v_cvt_pk_bf16_f32 v67, v76, v77
	v_cvt_pk_bf16_f32 v68, v78, v79
	v_cvt_pk_bf16_f32 v69, v72, v69
	flat_store_dwordx4 v[70:71], v[66:69]
	s_nop 1
	v_mul_f32_e32 v176, 0xbfb8aa3b, v62
	v_mul_f32_e32 v177, 0xbfb8aa3b, v63
	v_mul_f32_e32 v178, 0xbfb8aa3b, v64
	v_mul_f32_e32 v179, 0xbfb8aa3b, v65
	v_mul_f32_e32 v180, 0xbfb8aa3b, v54
	v_mul_f32_e32 v181, 0xbfb8aa3b, v55
	v_mul_f32_e32 v182, 0xbfb8aa3b, v56
	v_mul_f32_e32 v183, 0xbfb8aa3b, v57
	v_exp_f32_e32 v176, v176
	v_exp_f32_e32 v177, v177
	v_exp_f32_e32 v178, v178
	v_exp_f32_e32 v179, v179
	v_exp_f32_e32 v180, v180
	v_exp_f32_e32 v181, v181
	v_exp_f32_e32 v182, v182
	v_exp_f32_e32 v183, v183
	v_add_f32_e32 v176, 1.0, v176
	v_add_f32_e32 v177, 1.0, v177
	v_add_f32_e32 v178, 1.0, v178
	v_add_f32_e32 v179, 1.0, v179
	v_add_f32_e32 v180, 1.0, v180
	v_add_f32_e32 v181, 1.0, v181
	v_add_f32_e32 v182, 1.0, v182
	v_add_f32_e32 v183, 1.0, v183
	v_rcp_f32_e32 v176, v176
	v_rcp_f32_e32 v177, v177
	v_rcp_f32_e32 v178, v178
	v_rcp_f32_e32 v179, v179
	v_rcp_f32_e32 v180, v180
	v_rcp_f32_e32 v181, v181
	v_rcp_f32_e32 v182, v182
	v_rcp_f32_e32 v183, v183
	v_mul_f32_e32 v176, v62, v176
	v_mul_f32_e32 v177, v63, v177
	v_mul_f32_e32 v178, v64, v178
	v_mul_f32_e32 v179, v65, v179
	v_mul_f32_e32 v180, v54, v180
	v_mul_f32_e32 v181, v55, v181
	v_mul_f32_e32 v182, v56, v182
	v_mul_f32_e32 v183, v57, v183
	v_add_u32_e32 v66, s6, v149
	v_mad_i64_i32 v[66:67], s[50:51], v66, s16, v[142:143]
	v_lshl_add_u64 v[66:67], v[66:67], 0, s[48:49]
	v_lshl_add_u64 v[66:67], v[66:67], 0, s[26:27]
	v_mul_f32_e32 v58, v176, v58
	v_mul_f32_e32 v59, v177, v59
	v_mul_f32_e32 v60, v178, v60
	v_mul_f32_e32 v61, v179, v61
	v_mul_f32_e32 v62, v180, v50
	v_mul_f32_e32 v63, v181, v51
	v_lshl_add_u64 v[54:55], v[66:67], 0, v[0:1]
	v_mul_f32_e32 v56, v182, v52
	v_mul_f32_e32 v53, v183, v53
	v_cvt_pk_bf16_f32 v50, v58, v59
	v_cvt_pk_bf16_f32 v51, v60, v61
	v_cvt_pk_bf16_f32 v52, v62, v63
	v_cvt_pk_bf16_f32 v53, v56, v53
	flat_store_dwordx4 v[54:55], v[50:53]
	s_nop 1
	v_mul_f32_e32 v176, 0xbfb8aa3b, v46
	v_mul_f32_e32 v177, 0xbfb8aa3b, v47
	v_mul_f32_e32 v178, 0xbfb8aa3b, v48
	v_mul_f32_e32 v179, 0xbfb8aa3b, v49
	v_mul_f32_e32 v180, 0xbfb8aa3b, v38
	v_mul_f32_e32 v181, 0xbfb8aa3b, v39
	v_mul_f32_e32 v182, 0xbfb8aa3b, v40
	v_mul_f32_e32 v183, 0xbfb8aa3b, v41
	v_exp_f32_e32 v176, v176
	v_exp_f32_e32 v177, v177
	v_exp_f32_e32 v178, v178
	v_exp_f32_e32 v179, v179
	v_exp_f32_e32 v180, v180
	v_exp_f32_e32 v181, v181
	v_exp_f32_e32 v182, v182
	v_exp_f32_e32 v183, v183
	v_add_f32_e32 v176, 1.0, v176
	v_add_f32_e32 v177, 1.0, v177
	v_add_f32_e32 v178, 1.0, v178
	v_add_f32_e32 v179, 1.0, v179
	v_add_f32_e32 v180, 1.0, v180
	v_add_f32_e32 v181, 1.0, v181
	v_add_f32_e32 v182, 1.0, v182
	v_add_f32_e32 v183, 1.0, v183
	v_rcp_f32_e32 v176, v176
	v_rcp_f32_e32 v177, v177
	v_rcp_f32_e32 v178, v178
	v_rcp_f32_e32 v179, v179
	v_rcp_f32_e32 v180, v180
	v_rcp_f32_e32 v181, v181
	v_rcp_f32_e32 v182, v182
	v_rcp_f32_e32 v183, v183
	v_mul_f32_e32 v176, v46, v176
	v_mul_f32_e32 v177, v47, v177
	v_mul_f32_e32 v178, v48, v178
	v_mul_f32_e32 v179, v49, v179
	v_mul_f32_e32 v180, v38, v180
	v_mul_f32_e32 v181, v39, v181
	v_mul_f32_e32 v182, v40, v182
	v_mul_f32_e32 v183, v41, v183
	v_add_u32_e32 v50, s6, v150
	v_mad_i64_i32 v[50:51], s[50:51], v50, s16, v[142:143]
	v_lshl_add_u64 v[50:51], v[50:51], 0, s[48:49]
	v_lshl_add_u64 v[50:51], v[50:51], 0, s[26:27]
	v_mul_f32_e32 v42, v176, v42
	v_mul_f32_e32 v43, v177, v43
	v_mul_f32_e32 v44, v178, v44
	v_mul_f32_e32 v45, v179, v45
	v_mul_f32_e32 v46, v180, v34
	v_mul_f32_e32 v47, v181, v35
	v_lshl_add_u64 v[38:39], v[50:51], 0, v[0:1]
	v_mul_f32_e32 v40, v182, v36
	v_mul_f32_e32 v37, v183, v37
	v_cvt_pk_bf16_f32 v34, v42, v43
	v_cvt_pk_bf16_f32 v35, v44, v45
	v_cvt_pk_bf16_f32 v36, v46, v47
	v_cvt_pk_bf16_f32 v37, v40, v37
	flat_store_dwordx4 v[38:39], v[34:37]
	s_nop 1
	v_mul_f32_e32 v176, 0xbfb8aa3b, v30
	v_mul_f32_e32 v177, 0xbfb8aa3b, v31
	v_mul_f32_e32 v178, 0xbfb8aa3b, v32
	v_mul_f32_e32 v179, 0xbfb8aa3b, v33
	v_mul_f32_e32 v180, 0xbfb8aa3b, v22
	v_mul_f32_e32 v181, 0xbfb8aa3b, v23
	v_mul_f32_e32 v182, 0xbfb8aa3b, v24
	v_mul_f32_e32 v183, 0xbfb8aa3b, v25
	v_exp_f32_e32 v176, v176
	v_exp_f32_e32 v177, v177
	v_exp_f32_e32 v178, v178
	v_exp_f32_e32 v179, v179
	v_exp_f32_e32 v180, v180
	v_exp_f32_e32 v181, v181
	v_exp_f32_e32 v182, v182
	v_exp_f32_e32 v183, v183
	v_add_f32_e32 v176, 1.0, v176
	v_add_f32_e32 v177, 1.0, v177
	v_add_f32_e32 v178, 1.0, v178
	v_add_f32_e32 v179, 1.0, v179
	v_add_f32_e32 v180, 1.0, v180
	v_add_f32_e32 v181, 1.0, v181
	v_add_f32_e32 v182, 1.0, v182
	v_add_f32_e32 v183, 1.0, v183
	v_rcp_f32_e32 v176, v176
	v_rcp_f32_e32 v177, v177
	v_rcp_f32_e32 v178, v178
	v_rcp_f32_e32 v179, v179
	v_rcp_f32_e32 v180, v180
	v_rcp_f32_e32 v181, v181
	v_rcp_f32_e32 v182, v182
	v_rcp_f32_e32 v183, v183
	v_mul_f32_e32 v176, v30, v176
	v_mul_f32_e32 v177, v31, v177
	v_mul_f32_e32 v178, v32, v178
	v_mul_f32_e32 v179, v33, v179
	v_mul_f32_e32 v180, v22, v180
	v_mul_f32_e32 v181, v23, v181
	v_mul_f32_e32 v182, v24, v182
	v_mul_f32_e32 v183, v25, v183
	v_add_u32_e32 v34, s6, v151
	v_mad_i64_i32 v[34:35], s[50:51], v34, s16, v[142:143]
	v_lshl_add_u64 v[34:35], v[34:35], 0, s[48:49]
	v_lshl_add_u64 v[34:35], v[34:35], 0, s[26:27]
	v_mul_f32_e32 v26, v176, v26
	v_mul_f32_e32 v27, v177, v27
	v_mul_f32_e32 v28, v178, v28
	v_mul_f32_e32 v29, v179, v29
	v_mul_f32_e32 v30, v180, v18
	v_mul_f32_e32 v31, v181, v19
	v_lshl_add_u64 v[22:23], v[34:35], 0, v[0:1]
	v_mul_f32_e32 v24, v182, v20
	v_mul_f32_e32 v21, v183, v21
	v_cvt_pk_bf16_f32 v18, v26, v27
	v_cvt_pk_bf16_f32 v19, v28, v29
	v_cvt_pk_bf16_f32 v20, v30, v31
	v_cvt_pk_bf16_f32 v21, v24, v21
	flat_store_dwordx4 v[22:23], v[18:21]
	s_nop 1
	v_mul_f32_e32 v176, 0xbfb8aa3b, v14
	v_mul_f32_e32 v177, 0xbfb8aa3b, v15
	v_mul_f32_e32 v178, 0xbfb8aa3b, v16
	v_mul_f32_e32 v179, 0xbfb8aa3b, v17
	v_mul_f32_e32 v180, 0xbfb8aa3b, v6
	v_mul_f32_e32 v181, 0xbfb8aa3b, v7
	v_mul_f32_e32 v182, 0xbfb8aa3b, v8
	v_mul_f32_e32 v183, 0xbfb8aa3b, v9
	v_exp_f32_e32 v176, v176
	v_exp_f32_e32 v177, v177
	v_exp_f32_e32 v178, v178
	v_exp_f32_e32 v179, v179
	v_exp_f32_e32 v180, v180
	v_exp_f32_e32 v181, v181
	v_exp_f32_e32 v182, v182
	v_exp_f32_e32 v183, v183
	v_add_f32_e32 v176, 1.0, v176
	v_add_f32_e32 v177, 1.0, v177
	v_add_f32_e32 v178, 1.0, v178
	v_add_f32_e32 v179, 1.0, v179
	v_add_f32_e32 v180, 1.0, v180
	v_add_f32_e32 v181, 1.0, v181
	v_add_f32_e32 v182, 1.0, v182
	v_add_f32_e32 v183, 1.0, v183
	v_rcp_f32_e32 v176, v176
	v_rcp_f32_e32 v177, v177
	v_rcp_f32_e32 v178, v178
	v_rcp_f32_e32 v179, v179
	v_rcp_f32_e32 v180, v180
	v_rcp_f32_e32 v181, v181
	v_rcp_f32_e32 v182, v182
	v_rcp_f32_e32 v183, v183
	v_mul_f32_e32 v176, v14, v176
	v_mul_f32_e32 v177, v15, v177
	v_mul_f32_e32 v178, v16, v178
	v_mul_f32_e32 v179, v17, v179
	v_mul_f32_e32 v180, v6, v180
	v_mul_f32_e32 v181, v7, v181
	v_mul_f32_e32 v182, v8, v182
	v_mul_f32_e32 v183, v9, v183
	v_add_u32_e32 v18, s6, v152
	v_mad_i64_i32 v[18:19], s[50:51], v18, s16, v[142:143]
	v_lshl_add_u64 v[18:19], v[18:19], 0, s[48:49]
	v_lshl_add_u64 v[18:19], v[18:19], 0, s[26:27]
	s_mov_b64 s[48:49], -1
	v_mul_f32_e32 v10, v176, v10
	v_mul_f32_e32 v11, v177, v11
	v_mul_f32_e32 v12, v178, v12
	v_mul_f32_e32 v13, v179, v13
	v_mul_f32_e32 v14, v180, v2
	v_mul_f32_e32 v15, v181, v3
	v_lshl_add_u64 v[6:7], v[18:19], 0, v[0:1]
	v_mul_f32_e32 v8, v182, v4
	v_mul_f32_e32 v5, v183, v5
	v_cvt_pk_bf16_f32 v2, v10, v11
	v_cvt_pk_bf16_f32 v3, v12, v13
	v_cvt_pk_bf16_f32 v4, v14, v15
	v_cvt_pk_bf16_f32 v5, v8, v5
	flat_store_dwordx4 v[6:7], v[2:5]
	s_cbranch_vccnz .LBB0_428
	s_andn2_b64 vcc, exec, s[0:1]
	s_cbranch_vccnz .LBB0_427
	s_barrier
	s_branch .LBB0_427
